# norm phases: context-row modulation loads hoisted to the top of the row loop (one wait instead of four load/wait/store ladders)
# speedup vs baseline: 1.0010x; 1.0007x over previous
.LBB0_227:
	v_pk_mul_f32 v[34:35], v[52:53], v[52:53]
	v_pk_mul_f32 v[36:37], v[48:49], v[48:49]
	v_pk_fma_f32 v[34:35], v[50:51], v[50:51], v[34:35]
	v_pk_fma_f32 v[36:37], v[46:47], v[46:47], v[36:37]
	v_pk_add_f32 v[34:35], v[34:35], v[34:35] op_sel_hi:[0,1]
	v_pk_add_f32 v[36:37], v[36:37], v[36:37] op_sel_hi:[0,1]
	v_mul_f32_e32 v0, v44, v44
	v_mul_f32_e32 v41, v24, v24
	v_mul_f32_e32 v43, v25, v25
	s_waitcnt vmcnt(0)
	v_mov_b32_e32 v42, v21
	v_mov_b32_e32 v40, v21
	v_pk_fma_f32 v[38:39], v[44:45], v[44:45], v[0:1] op_sel_hi:[1,1,0]
	v_mul_f32_e32 v34, v18, v18
	v_mul_f32_e32 v36, v19, v19
	v_pk_add_f32 v[40:41], v[42:43], v[40:41]
	v_mul_f32_e32 v38, v20, v20
	v_pk_add_f32 v[34:35], v[36:37], v[34:35]
	v_mul_f32_e32 v36, v21, v21
	v_mov_b32_e32 v37, v41
	v_pk_add_f32 v[36:37], v[36:37], v[38:39]
	v_ashrrev_i32_e32 v93, 31, v92
	v_pk_add_f32 v[34:35], v[36:37], v[34:35]
	v_readlane_b32 s6, v253, 47
	v_add_f32_e32 v0, v34, v35
	ds_bpermute_b32 v34, v112, v0
	v_readlane_b32 s7, v253, 48
	s_waitcnt lgkmcnt(0)
	v_add_f32_e32 v0, v0, v34
	ds_bpermute_b32 v34, v113, v0
	v_lshl_add_u64 v[104:105], v[104:105], 0, s[6:7]
	s_waitcnt lgkmcnt(0)
	v_add_f32_e32 v0, v0, v34
	ds_bpermute_b32 v34, v114, v0
	s_waitcnt lgkmcnt(0)
	v_add_f32_e32 v0, v0, v34
	ds_bpermute_b32 v34, v115, v0
	s_waitcnt lgkmcnt(0)
	v_add_f32_e32 v0, v0, v34
	ds_bpermute_b32 v34, v116, v0
	s_waitcnt lgkmcnt(0)
	v_add_f32_e32 v0, v0, v34
	ds_bpermute_b32 v34, v117, v0
	s_waitcnt lgkmcnt(0)
	v_add_f32_e32 v0, v0, v34
	v_fmamk_f32 v0, v0, 0x3a800000, v150
	v_cmp_gt_f32_e32 vcc, s50, v0
	v_mul_f32_e32 v34, 0x4b800000, v0
	s_nop 0
	v_cndmask_b32_e32 v0, v0, v34, vcc
	v_rsq_f32_e32 v0, v0
	s_nop 0
	v_mul_f32_e32 v34, 0x45800000, v0
	v_cndmask_b32_e32 v0, v0, v34, vcc
	v_lshlrev_b64 v[34:35], 11, v[92:93]
	v_lshl_add_u64 v[38:39], v[100:101], 0, v[34:35]
	v_pk_mul_f32 v[32:33], v[32:33], v[0:1] op_sel_hi:[1,0]
	v_pk_mul_f32 v[30:31], v[30:31], v[0:1] op_sel_hi:[1,0]
	v_pk_mul_f32 v[32:33], v[4:5], v[32:33]
	v_pk_mul_f32 v[30:31], v[2:3], v[30:31]
	v_pk_mul_f32 v[28:29], v[28:29], v[0:1] op_sel_hi:[1,0]
	v_pk_mul_f32 v[26:27], v[26:27], v[0:1] op_sel_hi:[1,0]
	v_pk_mul_f32 v[28:29], v[8:9], v[28:29]
	v_pk_mul_f32 v[26:27], v[6:7], v[26:27]
	v_pk_mul_f32 v[24:25], v[24:25], v[0:1] op_sel_hi:[1,0]
	v_pk_mul_f32 v[22:23], v[22:23], v[0:1] op_sel_hi:[1,0]
	v_pk_mul_f32 v[24:25], v[12:13], v[24:25]
	v_pk_mul_f32 v[22:23], v[10:11], v[22:23]
	v_pk_mul_f32 v[20:21], v[20:21], v[0:1] op_sel_hi:[1,0]
	v_pk_mul_f32 v[18:19], v[18:19], v[0:1] op_sel_hi:[1,0]
	v_pk_mul_f32 v[20:21], v[16:17], v[20:21]
	v_pk_mul_f32 v[18:19], v[14:15], v[18:19]
	v_add_u32_e32 v92, s72, v92
	v_cmp_lt_i32_e32 vcc, s51, v92
	s_or_b64 s[2:3], vcc, s[2:3]
	s_waitcnt vmcnt(0)
	v_mov_b32_e32 v34, v204
	v_mov_b32_e32 v35, v205
	v_mov_b32_e32 v36, v206
	v_mov_b32_e32 v37, v207
	v_mov_b32_e32 v40, v208
	v_mov_b32_e32 v41, v209
	v_mov_b32_e32 v42, v210
	v_mov_b32_e32 v43, v211
	v_pk_add_f32 v[42:43], v[42:43], 1.0 op_sel_hi:[1,0]
	v_pk_add_f32 v[40:41], v[40:41], 1.0 op_sel_hi:[1,0]
	v_pk_fma_f32 v[32:33], v[42:43], v[32:33], v[36:37]
	v_pk_fma_f32 v[30:31], v[40:41], v[30:31], v[34:35]
	s_nop 0
	v_cvt_pk_bf16_f32 v30, v30, v31
	v_cvt_pk_bf16_f32 v31, v32, v33
	global_store_dwordx2 v[38:39], v[30:31], off
	s_nop 1
	v_mov_b32_e32 v30, v212
	v_mov_b32_e32 v31, v213
	v_mov_b32_e32 v32, v214
	v_mov_b32_e32 v33, v215
	s_nop 0
	v_mov_b32_e32 v34, v216
	v_mov_b32_e32 v35, v217
	v_mov_b32_e32 v36, v218
	v_mov_b32_e32 v37, v219
	v_pk_add_f32 v[36:37], v[36:37], 1.0 op_sel_hi:[1,0]
	v_pk_add_f32 v[34:35], v[34:35], 1.0 op_sel_hi:[1,0]
	v_pk_fma_f32 v[28:29], v[36:37], v[28:29], v[32:33]
	v_pk_fma_f32 v[26:27], v[34:35], v[26:27], v[30:31]
	s_nop 0
	v_cvt_pk_bf16_f32 v26, v26, v27
	v_cvt_pk_bf16_f32 v27, v28, v29
	global_store_dwordx2 v[38:39], v[26:27], off offset:512
	s_nop 1
	v_mov_b32_e32 v26, v220
	v_mov_b32_e32 v27, v221
	v_mov_b32_e32 v28, v222
	v_mov_b32_e32 v29, v223
	s_nop 0
	v_mov_b32_e32 v30, v224
	v_mov_b32_e32 v31, v225
	v_mov_b32_e32 v32, v226
	v_mov_b32_e32 v33, v227
	v_pk_add_f32 v[32:33], v[32:33], 1.0 op_sel_hi:[1,0]
	v_pk_add_f32 v[30:31], v[30:31], 1.0 op_sel_hi:[1,0]
	v_pk_fma_f32 v[24:25], v[32:33], v[24:25], v[28:29]
	v_pk_fma_f32 v[22:23], v[30:31], v[22:23], v[26:27]
	s_nop 0
	v_cvt_pk_bf16_f32 v22, v22, v23
	v_cvt_pk_bf16_f32 v23, v24, v25
	global_store_dwordx2 v[38:39], v[22:23], off offset:1024
	s_nop 1
	v_mov_b32_e32 v22, v228
	v_mov_b32_e32 v23, v229
	v_mov_b32_e32 v24, v230
	v_mov_b32_e32 v25, v231
	s_nop 0
	v_mov_b32_e32 v26, v236
	v_mov_b32_e32 v27, v237
	v_mov_b32_e32 v28, v238
	v_mov_b32_e32 v29, v239
	v_pk_add_f32 v[28:29], v[28:29], 1.0 op_sel_hi:[1,0]
	v_pk_add_f32 v[26:27], v[26:27], 1.0 op_sel_hi:[1,0]
	v_pk_fma_f32 v[20:21], v[28:29], v[20:21], v[24:25]
	v_pk_fma_f32 v[18:19], v[26:27], v[18:19], v[22:23]
	s_nop 0
	v_cvt_pk_bf16_f32 v18, v18, v19
	v_cvt_pk_bf16_f32 v19, v20, v21
	global_store_dwordx2 v[38:39], v[18:19], off offset:1536
	s_andn2_b64 exec, exec, s[2:3]
	s_cbranch_execz .LBB0_241
.LBB0_228:
	v_add_u32_e32 v22, 0xffffc000, v92
	v_ashrrev_i32_e32 v23, 31, v22
	v_lshlrev_b64 v[18:19], 12, v[22:23]
	v_lshl_add_u64 v[106:107], v[102:103], 0, v[18:19]
	global_load_dwordx4 v[204:207], v[96:97], off
	global_load_dwordx4 v[208:211], v[98:99], off
	global_load_dwordx4 v[212:215], v[96:97], off offset:1024
	global_load_dwordx4 v[216:219], v[98:99], off offset:1024
	global_load_dwordx4 v[220:223], v[96:97], off offset:2048
	global_load_dwordx4 v[224:227], v[98:99], off offset:2048
	global_load_dwordx4 v[228:231], v[96:97], off offset:3072
	global_load_dwordx4 v[236:239], v[98:99], off offset:3072
	global_load_dwordx4 v[34:37], v[106:107], off
	global_load_dwordx4 v[38:41], v[106:107], off offset:1024
	global_load_dwordx4 v[42:45], v[106:107], off offset:2048
	global_load_dwordx4 v[18:21], v[106:107], off offset:3072
	v_readlane_b32 s6, v254, 10
	v_readlane_b32 s7, v254, 11
	s_and_b64 vcc, exec, s[6:7]
	s_cbranch_vccz .LBB0_237
	v_lshlrev_b64 v[22:23], 10, v[22:23]
	v_lshl_add_u64 v[108:109], v[22:23], 2, v[94:95]
	s_mov_b32 s10, 0
	v_mov_b64_e32 v[110:111], v[104:105]
	s_waitcnt vmcnt(3)
	v_mov_b32_e32 v30, v34
	v_mov_b32_e32 v31, v35
	v_mov_b32_e32 v32, v36
	v_mov_b32_e32 v33, v37
	s_waitcnt vmcnt(2)
	v_mov_b32_e32 v26, v38
	v_mov_b32_e32 v27, v39
	v_mov_b32_e32 v28, v40
	v_mov_b32_e32 v29, v41
	s_waitcnt vmcnt(1)
	v_mov_b32_e32 v22, v42
	v_mov_b32_e32 v23, v43
	v_mov_b32_e32 v24, v44
	v_mov_b32_e32 v25, v45
	s_branch .LBB0_231

.LBB0_703:
	s_waitcnt vmcnt(3)
	v_pk_mul_f32 v[34:35], v[58:59], v[58:59]
	v_pk_mul_f32 v[36:37], v[54:55], v[54:55]
	v_pk_fma_f32 v[34:35], v[56:57], v[56:57], v[34:35]
	v_pk_fma_f32 v[36:37], v[52:53], v[52:53], v[36:37]
	v_pk_add_f32 v[34:35], v[34:35], v[34:35] op_sel_hi:[0,1]
	v_pk_add_f32 v[36:37], v[36:37], v[36:37] op_sel_hi:[0,1]
	v_mul_f32_e32 v0, v50, v50
	s_waitcnt vmcnt(2)
	v_mul_f32_e32 v41, v24, v24
	s_waitcnt vmcnt(1)
	v_mul_f32_e32 v43, v25, v25
	v_mov_b32_e32 v42, v21
	v_mov_b32_e32 v40, v21
	v_pk_fma_f32 v[38:39], v[50:51], v[50:51], v[0:1] op_sel_hi:[1,1,0]
	v_mul_f32_e32 v34, v18, v18
	v_mul_f32_e32 v36, v19, v19
	v_pk_add_f32 v[40:41], v[42:43], v[40:41]
	v_mul_f32_e32 v38, v20, v20
	v_pk_add_f32 v[34:35], v[36:37], v[34:35]
	v_mul_f32_e32 v36, v21, v21
	v_mov_b32_e32 v37, v41
	v_pk_add_f32 v[36:37], v[36:37], v[38:39]
	v_ashrrev_i32_e32 v99, 31, v98
	v_pk_add_f32 v[34:35], v[36:37], v[34:35]
	v_readlane_b32 s4, v253, 47
	v_add_f32_e32 v0, v34, v35
	ds_bpermute_b32 v34, v118, v0
	v_readlane_b32 s5, v253, 48
	s_waitcnt lgkmcnt(0)
	v_add_f32_e32 v0, v0, v34
	ds_bpermute_b32 v34, v119, v0
	v_lshl_add_u64 v[110:111], v[110:111], 0, s[4:5]
	s_waitcnt lgkmcnt(0)
	v_add_f32_e32 v0, v0, v34
	ds_bpermute_b32 v34, v120, v0
	s_waitcnt lgkmcnt(0)
	v_add_f32_e32 v0, v0, v34
	ds_bpermute_b32 v34, v121, v0
	s_waitcnt lgkmcnt(0)
	v_add_f32_e32 v0, v0, v34
	ds_bpermute_b32 v34, v122, v0
	s_waitcnt lgkmcnt(0)
	v_add_f32_e32 v0, v0, v34
	ds_bpermute_b32 v34, v123, v0
	s_waitcnt lgkmcnt(0)
	v_add_f32_e32 v0, v0, v34
	v_fmamk_f32 v0, v0, 0x3a800000, v150
	v_cmp_gt_f32_e32 vcc, s50, v0
	v_mul_f32_e32 v34, 0x4b800000, v0
	s_nop 0
	v_cndmask_b32_e32 v0, v0, v34, vcc
	v_rsq_f32_e32 v0, v0
	s_nop 0
	v_mul_f32_e32 v34, 0x45800000, v0
	v_cndmask_b32_e32 v0, v0, v34, vcc
	v_lshlrev_b64 v[34:35], 11, v[98:99]
	v_lshl_add_u64 v[38:39], v[106:107], 0, v[34:35]
	v_pk_mul_f32 v[32:33], v[32:33], v[0:1] op_sel_hi:[1,0]
	v_pk_mul_f32 v[30:31], v[30:31], v[0:1] op_sel_hi:[1,0]
	v_pk_mul_f32 v[32:33], v[4:5], v[32:33]
	v_pk_mul_f32 v[30:31], v[2:3], v[30:31]
	v_pk_mul_f32 v[28:29], v[28:29], v[0:1] op_sel_hi:[1,0]
	v_pk_mul_f32 v[26:27], v[26:27], v[0:1] op_sel_hi:[1,0]
	v_pk_mul_f32 v[28:29], v[8:9], v[28:29]
	v_pk_mul_f32 v[26:27], v[6:7], v[26:27]
	v_pk_mul_f32 v[24:25], v[24:25], v[0:1] op_sel_hi:[1,0]
	v_pk_mul_f32 v[22:23], v[22:23], v[0:1] op_sel_hi:[1,0]
	v_pk_mul_f32 v[24:25], v[12:13], v[24:25]
	v_pk_mul_f32 v[22:23], v[10:11], v[22:23]
	v_pk_mul_f32 v[20:21], v[20:21], v[0:1] op_sel_hi:[1,0]
	v_pk_mul_f32 v[18:19], v[18:19], v[0:1] op_sel_hi:[1,0]
	v_pk_mul_f32 v[20:21], v[16:17], v[20:21]
	v_pk_mul_f32 v[18:19], v[14:15], v[18:19]
	v_add_u32_e32 v98, s72, v98
	v_cmp_lt_i32_e32 vcc, s51, v98
	s_or_b64 s[2:3], vcc, s[2:3]
	s_waitcnt vmcnt(0)
	v_mov_b32_e32 v34, v204
	v_mov_b32_e32 v35, v205
	v_mov_b32_e32 v36, v206
	v_mov_b32_e32 v37, v207
	v_mov_b32_e32 v40, v208
	v_mov_b32_e32 v41, v209
	v_mov_b32_e32 v42, v210
	v_mov_b32_e32 v43, v211
	v_pk_add_f32 v[42:43], v[42:43], 1.0 op_sel_hi:[1,0]
	v_pk_add_f32 v[40:41], v[40:41], 1.0 op_sel_hi:[1,0]
	v_pk_fma_f32 v[32:33], v[42:43], v[32:33], v[36:37]
	v_pk_fma_f32 v[30:31], v[40:41], v[30:31], v[34:35]
	s_nop 0
	v_cvt_pk_bf16_f32 v30, v30, v31
	v_cvt_pk_bf16_f32 v31, v32, v33
	global_store_dwordx2 v[38:39], v[30:31], off
	s_nop 1
	v_mov_b32_e32 v30, v212
	v_mov_b32_e32 v31, v213
	v_mov_b32_e32 v32, v214
	v_mov_b32_e32 v33, v215
	s_nop 0
	v_mov_b32_e32 v34, v216
	v_mov_b32_e32 v35, v217
	v_mov_b32_e32 v36, v218
	v_mov_b32_e32 v37, v219
	v_pk_add_f32 v[36:37], v[36:37], 1.0 op_sel_hi:[1,0]
	v_pk_add_f32 v[34:35], v[34:35], 1.0 op_sel_hi:[1,0]
	v_pk_fma_f32 v[28:29], v[36:37], v[28:29], v[32:33]
	v_pk_fma_f32 v[26:27], v[34:35], v[26:27], v[30:31]
	s_nop 0
	v_cvt_pk_bf16_f32 v26, v26, v27
	v_cvt_pk_bf16_f32 v27, v28, v29
	global_store_dwordx2 v[38:39], v[26:27], off offset:512
	s_nop 1
	v_mov_b32_e32 v26, v220
	v_mov_b32_e32 v27, v221
	v_mov_b32_e32 v28, v222
	v_mov_b32_e32 v29, v223
	s_nop 0
	v_mov_b32_e32 v30, v224
	v_mov_b32_e32 v31, v225
	v_mov_b32_e32 v32, v226
	v_mov_b32_e32 v33, v227
	v_pk_add_f32 v[32:33], v[32:33], 1.0 op_sel_hi:[1,0]
	v_pk_add_f32 v[30:31], v[30:31], 1.0 op_sel_hi:[1,0]
	v_pk_fma_f32 v[24:25], v[32:33], v[24:25], v[28:29]
	v_pk_fma_f32 v[22:23], v[30:31], v[22:23], v[26:27]
	s_nop 0
	v_cvt_pk_bf16_f32 v22, v22, v23
	v_cvt_pk_bf16_f32 v23, v24, v25
	global_store_dwordx2 v[38:39], v[22:23], off offset:1024
	s_nop 1
	v_mov_b32_e32 v22, v228
	v_mov_b32_e32 v23, v229
	v_mov_b32_e32 v24, v230
	v_mov_b32_e32 v25, v231
	s_nop 0
	v_mov_b32_e32 v26, v236
	v_mov_b32_e32 v27, v237
	v_mov_b32_e32 v28, v238
	v_mov_b32_e32 v29, v239
	v_pk_add_f32 v[28:29], v[28:29], 1.0 op_sel_hi:[1,0]
	v_pk_add_f32 v[26:27], v[26:27], 1.0 op_sel_hi:[1,0]
	v_pk_fma_f32 v[20:21], v[28:29], v[20:21], v[24:25]
	v_pk_fma_f32 v[18:19], v[26:27], v[18:19], v[22:23]
	s_nop 0
	v_cvt_pk_bf16_f32 v18, v18, v19
	v_cvt_pk_bf16_f32 v19, v20, v21
	global_store_dwordx2 v[38:39], v[18:19], off offset:1536
	s_andn2_b64 exec, exec, s[2:3]
	s_cbranch_execz .LBB0_720
.LBB0_704:
	v_add_u32_e32 v32, 0xffffc000, v98
	v_ashrrev_i32_e32 v33, 31, v32
	v_lshlrev_b64 v[18:19], 12, v[32:33]
	v_lshl_add_u64 v[112:113], v[108:109], 0, v[18:19]
	global_load_dwordx4 v[204:207], v[102:103], off
	global_load_dwordx4 v[208:211], v[104:105], off
	global_load_dwordx4 v[212:215], v[102:103], off offset:1024
	global_load_dwordx4 v[216:219], v[104:105], off offset:1024
	global_load_dwordx4 v[220:223], v[102:103], off offset:2048
	global_load_dwordx4 v[224:227], v[104:105], off offset:2048
	global_load_dwordx4 v[228:231], v[102:103], off offset:3072
	global_load_dwordx4 v[236:239], v[104:105], off offset:3072
	global_load_dwordx4 v[34:37], v[112:113], off
	global_load_dwordx4 v[38:41], v[112:113], off offset:1024
	global_load_dwordx4 v[42:45], v[112:113], off offset:2048
	global_load_dwordx4 v[46:49], v[112:113], off offset:3072
	s_cmp_lt_i32 s25, 3
	s_cbranch_scc1 .LBB0_706
	s_cmp_lg_u32 s25, 3
	s_mov_b64 s[4:5], -1
	s_cselect_b64 s[6:7], -1, 0
	s_cbranch_execz .LBB0_707
	s_branch .LBB0_708
